# nt hint: input-projection epilogue stores + residual loads of the output projections
# baseline (speedup 1.0000x reference)
.LBB0_951:
	s_mul_i32 s15, s28, 0x3000
	s_mul_hi_i32 s17, s28, 0x3000
	s_and_b64 s[24:25], s[24:25], exec
	s_cselect_b32 s29, s17, 0
	s_cselect_b32 s28, s15, 0x6000
	s_lshl_b64 s[34:35], s[34:35], 14
	s_add_u32 s24, s30, s34
	s_addc_u32 s25, s31, s35
	s_lshl_b64 s[28:29], s[28:29], 2
	v_lshl_or_b32 v176, s62, 8, v163
	s_add_u32 s28, s20, s28
	v_ashrrev_i32_e32 v177, 31, v176
	s_addc_u32 s29, s21, s29
	v_lshl_add_u64 v[134:135], v[150:151], 0, v[176:177]
	v_lshl_add_u64 v[130:131], v[176:177], 2, s[28:29]
	v_lshlrev_b64 v[186:187], 2, v[134:135]
	v_add_co_u32_e32 v132, vcc, s58, v130
	v_lshl_add_u64 v[188:189], s[24:25], 0, v[186:187]
	s_nop 0
	v_addc_co_u32_e32 v133, vcc, 0, v131, vcc
	global_load_dwordx4 v[182:185], v[188:189], off nt
	global_load_dwordx4 v[142:145], v[132:133], off nt
	s_add_u32 s26, s26, s34
	s_addc_u32 s27, s27, s35
	v_lshl_add_u64 v[130:131], v[130:131], 0, s[12:13]
	v_lshl_add_u64 v[186:187], s[26:27], 0, v[186:187]
	global_load_dwordx4 v[138:141], v[130:131], off offset:64 nt
	global_load_dwordx4 v[134:137], v[130:131], off offset:512 nt
	s_nop 0
	global_load_dwordx4 v[130:133], v[130:131], off offset:576 nt
	s_andn2_b64 vcc, exec, s[0:1]
	s_mov_b64 s[0:1], -1
	s_waitcnt vmcnt(0)
	v_pk_fma_f32 v[128:129], v[128:129], v[144:145], v[184:185]
	v_pk_fma_f32 v[126:127], v[126:127], v[142:143], v[182:183]
	global_store_dwordx4 v[186:187], v[126:129], off
	global_load_dwordx4 v[126:129], v[188:189], off offset:64 nt
	s_waitcnt vmcnt(0)
	v_pk_fma_f32 v[124:125], v[124:125], v[140:141], v[128:129]
	v_pk_fma_f32 v[122:123], v[122:123], v[138:139], v[126:127]
	global_store_dwordx4 v[186:187], v[122:125], off offset:64
	global_load_dwordx4 v[122:125], v[188:189], off offset:512 nt
	s_waitcnt vmcnt(0)
	v_pk_fma_f32 v[120:121], v[120:121], v[136:137], v[124:125]
	v_pk_fma_f32 v[118:119], v[118:119], v[134:135], v[122:123]
	global_store_dwordx4 v[186:187], v[118:121], off offset:512
	global_load_dwordx4 v[118:121], v[188:189], off offset:576 nt
	v_lshl_add_u64 v[122:123], v[152:153], 0, v[176:177]
	v_lshlrev_b64 v[122:123], 2, v[122:123]
	v_lshl_add_u64 v[124:125], s[24:25], 0, v[122:123]
	s_waitcnt vmcnt(0)
	v_pk_fma_f32 v[108:109], v[108:109], v[132:133], v[120:121]
	v_pk_fma_f32 v[106:107], v[106:107], v[130:131], v[118:119]
	global_store_dwordx4 v[186:187], v[106:109], off offset:576
	global_load_dwordx4 v[106:109], v[124:125], off nt
	v_lshl_add_u64 v[118:119], s[26:27], 0, v[122:123]
	s_waitcnt vmcnt(0)
	v_pk_fma_f32 v[108:109], v[116:117], v[144:145], v[108:109]
	v_pk_fma_f32 v[106:107], v[114:115], v[142:143], v[106:107]
	global_store_dwordx4 v[118:119], v[106:109], off
	global_load_dwordx4 v[106:109], v[124:125], off offset:64 nt
	s_waitcnt vmcnt(0)
	v_pk_fma_f32 v[108:109], v[112:113], v[140:141], v[108:109]
	v_pk_fma_f32 v[106:107], v[110:111], v[138:139], v[106:107]
	global_store_dwordx4 v[118:119], v[106:109], off offset:64
	global_load_dwordx4 v[106:109], v[124:125], off offset:512 nt
	s_waitcnt vmcnt(0)
	v_pk_fma_f32 v[104:105], v[104:105], v[136:137], v[108:109]
	v_pk_fma_f32 v[102:103], v[102:103], v[134:135], v[106:107]
	global_store_dwordx4 v[118:119], v[102:105], off offset:512
	global_load_dwordx4 v[102:105], v[124:125], off offset:576 nt
	v_lshl_add_u64 v[106:107], v[154:155], 0, v[176:177]
	v_lshlrev_b64 v[106:107], 2, v[106:107]
	v_lshl_add_u64 v[108:109], s[24:25], 0, v[106:107]
	s_waitcnt vmcnt(0)
	v_pk_fma_f32 v[92:93], v[92:93], v[132:133], v[104:105]
	v_pk_fma_f32 v[90:91], v[90:91], v[130:131], v[102:103]
	global_store_dwordx4 v[118:119], v[90:93], off offset:576
	global_load_dwordx4 v[90:93], v[108:109], off nt
	v_lshl_add_u64 v[102:103], s[26:27], 0, v[106:107]
	s_waitcnt vmcnt(0)
	v_pk_fma_f32 v[92:93], v[100:101], v[144:145], v[92:93]
	v_pk_fma_f32 v[90:91], v[98:99], v[142:143], v[90:91]
	global_store_dwordx4 v[102:103], v[90:93], off
	global_load_dwordx4 v[90:93], v[108:109], off offset:64 nt
	s_waitcnt vmcnt(0)
	v_pk_fma_f32 v[92:93], v[96:97], v[140:141], v[92:93]
	v_pk_fma_f32 v[90:91], v[94:95], v[138:139], v[90:91]
	global_store_dwordx4 v[102:103], v[90:93], off offset:64
	global_load_dwordx4 v[90:93], v[108:109], off offset:512 nt
	s_waitcnt vmcnt(0)
	v_pk_fma_f32 v[88:89], v[88:89], v[136:137], v[92:93]
	v_pk_fma_f32 v[86:87], v[86:87], v[134:135], v[90:91]
	global_store_dwordx4 v[102:103], v[86:89], off offset:512
	global_load_dwordx4 v[86:89], v[108:109], off offset:576 nt
	v_lshl_add_u64 v[90:91], v[156:157], 0, v[176:177]
	v_lshlrev_b64 v[90:91], 2, v[90:91]
	v_lshl_add_u64 v[92:93], s[24:25], 0, v[90:91]
	s_waitcnt vmcnt(0)
	v_pk_fma_f32 v[76:77], v[76:77], v[132:133], v[88:89]
	v_pk_fma_f32 v[74:75], v[74:75], v[130:131], v[86:87]
	global_store_dwordx4 v[102:103], v[74:77], off offset:576
	global_load_dwordx4 v[74:77], v[92:93], off nt
	v_lshl_add_u64 v[86:87], s[26:27], 0, v[90:91]
	s_waitcnt vmcnt(0)
	v_pk_fma_f32 v[76:77], v[84:85], v[144:145], v[76:77]
	v_pk_fma_f32 v[74:75], v[82:83], v[142:143], v[74:75]
	global_store_dwordx4 v[86:87], v[74:77], off
	global_load_dwordx4 v[74:77], v[92:93], off offset:64 nt
	s_waitcnt vmcnt(0)
	v_pk_fma_f32 v[76:77], v[80:81], v[140:141], v[76:77]
	v_pk_fma_f32 v[74:75], v[78:79], v[138:139], v[74:75]
	global_store_dwordx4 v[86:87], v[74:77], off offset:64
	global_load_dwordx4 v[74:77], v[92:93], off offset:512 nt
	s_waitcnt vmcnt(0)
	v_pk_fma_f32 v[72:73], v[72:73], v[136:137], v[76:77]
	v_pk_fma_f32 v[70:71], v[70:71], v[134:135], v[74:75]
	global_store_dwordx4 v[86:87], v[70:73], off offset:512
	global_load_dwordx4 v[70:73], v[92:93], off offset:576 nt
	v_lshl_add_u64 v[74:75], v[158:159], 0, v[176:177]
	v_lshlrev_b64 v[74:75], 2, v[74:75]
	v_lshl_add_u64 v[76:77], s[24:25], 0, v[74:75]
	s_waitcnt vmcnt(0)
	v_pk_fma_f32 v[68:69], v[68:69], v[132:133], v[72:73]
	v_pk_fma_f32 v[66:67], v[66:67], v[130:131], v[70:71]
	global_store_dwordx4 v[86:87], v[66:69], off offset:576
	global_load_dwordx4 v[66:69], v[76:77], off nt
	v_lshl_add_u64 v[70:71], s[26:27], 0, v[74:75]
	s_waitcnt vmcnt(0)
	v_pk_fma_f32 v[64:65], v[64:65], v[144:145], v[68:69]
	v_pk_fma_f32 v[62:63], v[62:63], v[142:143], v[66:67]
	global_store_dwordx4 v[70:71], v[62:65], off
	global_load_dwordx4 v[62:65], v[76:77], off offset:64 nt
	s_waitcnt vmcnt(0)
	v_pk_fma_f32 v[60:61], v[60:61], v[140:141], v[64:65]
	v_pk_fma_f32 v[58:59], v[58:59], v[138:139], v[62:63]
	global_store_dwordx4 v[70:71], v[58:61], off offset:64
	global_load_dwordx4 v[58:61], v[76:77], off offset:512 nt
	s_waitcnt vmcnt(0)
	v_pk_fma_f32 v[56:57], v[56:57], v[136:137], v[60:61]
	v_pk_fma_f32 v[54:55], v[54:55], v[134:135], v[58:59]
	global_store_dwordx4 v[70:71], v[54:57], off offset:512
	global_load_dwordx4 v[54:57], v[76:77], off offset:576 nt
	v_lshl_add_u64 v[58:59], v[160:161], 0, v[176:177]
	v_lshlrev_b64 v[58:59], 2, v[58:59]
	v_lshl_add_u64 v[60:61], s[24:25], 0, v[58:59]
	s_waitcnt vmcnt(0)
	v_pk_fma_f32 v[44:45], v[44:45], v[132:133], v[56:57]
	v_pk_fma_f32 v[42:43], v[42:43], v[130:131], v[54:55]
	global_store_dwordx4 v[70:71], v[42:45], off offset:576
	global_load_dwordx4 v[42:45], v[60:61], off nt
	v_lshl_add_u64 v[54:55], s[26:27], 0, v[58:59]
	s_waitcnt vmcnt(0)
	v_pk_fma_f32 v[44:45], v[52:53], v[144:145], v[44:45]
	v_pk_fma_f32 v[42:43], v[50:51], v[142:143], v[42:43]
	global_store_dwordx4 v[54:55], v[42:45], off
	global_load_dwordx4 v[42:45], v[60:61], off offset:64 nt
	s_waitcnt vmcnt(0)
	v_pk_fma_f32 v[44:45], v[48:49], v[140:141], v[44:45]
	v_pk_fma_f32 v[42:43], v[46:47], v[138:139], v[42:43]
	global_store_dwordx4 v[54:55], v[42:45], off offset:64
	global_load_dwordx4 v[42:45], v[60:61], off offset:512 nt
	s_waitcnt vmcnt(0)
	v_pk_fma_f32 v[40:41], v[40:41], v[136:137], v[44:45]
	v_pk_fma_f32 v[38:39], v[38:39], v[134:135], v[42:43]
	global_store_dwordx4 v[54:55], v[38:41], off offset:512
	global_load_dwordx4 v[38:41], v[60:61], off offset:576 nt
	v_lshl_add_u64 v[42:43], v[164:165], 0, v[176:177]
	v_lshlrev_b64 v[42:43], 2, v[42:43]
	v_lshl_add_u64 v[44:45], s[24:25], 0, v[42:43]
	s_waitcnt vmcnt(0)
	v_pk_fma_f32 v[28:29], v[28:29], v[132:133], v[40:41]
	v_pk_fma_f32 v[26:27], v[26:27], v[130:131], v[38:39]
	global_store_dwordx4 v[54:55], v[26:29], off offset:576
	global_load_dwordx4 v[26:29], v[44:45], off nt
	v_lshl_add_u64 v[38:39], s[26:27], 0, v[42:43]
	s_waitcnt vmcnt(0)
	v_pk_fma_f32 v[28:29], v[36:37], v[144:145], v[28:29]
	v_pk_fma_f32 v[26:27], v[34:35], v[142:143], v[26:27]
	global_store_dwordx4 v[38:39], v[26:29], off
	global_load_dwordx4 v[26:29], v[44:45], off offset:64 nt
	s_waitcnt vmcnt(0)
	v_pk_fma_f32 v[28:29], v[32:33], v[140:141], v[28:29]
	v_pk_fma_f32 v[26:27], v[30:31], v[138:139], v[26:27]
	global_store_dwordx4 v[38:39], v[26:29], off offset:64
	global_load_dwordx4 v[26:29], v[44:45], off offset:512 nt
	s_waitcnt vmcnt(0)
	v_pk_fma_f32 v[24:25], v[24:25], v[136:137], v[28:29]
	v_pk_fma_f32 v[22:23], v[22:23], v[134:135], v[26:27]
	global_store_dwordx4 v[38:39], v[22:25], off offset:512
	global_load_dwordx4 v[22:25], v[44:45], off offset:576 nt
	v_lshl_add_u64 v[26:27], v[166:167], 0, v[176:177]
	v_lshlrev_b64 v[26:27], 2, v[26:27]
	v_lshl_add_u64 v[28:29], s[24:25], 0, v[26:27]
	s_waitcnt vmcnt(0)
	v_pk_fma_f32 v[12:13], v[12:13], v[132:133], v[24:25]
	v_pk_fma_f32 v[10:11], v[10:11], v[130:131], v[22:23]
	global_store_dwordx4 v[38:39], v[10:13], off offset:576
	global_load_dwordx4 v[10:13], v[28:29], off nt
	v_lshl_add_u64 v[22:23], s[26:27], 0, v[26:27]
	s_waitcnt vmcnt(0)
	v_pk_fma_f32 v[12:13], v[20:21], v[144:145], v[12:13]
	v_pk_fma_f32 v[10:11], v[18:19], v[142:143], v[10:11]
	global_store_dwordx4 v[22:23], v[10:13], off
	global_load_dwordx4 v[10:13], v[28:29], off offset:64 nt
	s_waitcnt vmcnt(0)
	v_pk_fma_f32 v[12:13], v[16:17], v[140:141], v[12:13]
	v_pk_fma_f32 v[10:11], v[14:15], v[138:139], v[10:11]
	global_store_dwordx4 v[22:23], v[10:13], off offset:64
	global_load_dwordx4 v[10:13], v[28:29], off offset:512 nt
	s_waitcnt vmcnt(0)
	v_pk_fma_f32 v[8:9], v[8:9], v[136:137], v[12:13]
	v_pk_fma_f32 v[6:7], v[6:7], v[134:135], v[10:11]
	global_store_dwordx4 v[22:23], v[6:9], off offset:512
	global_load_dwordx4 v[6:9], v[28:29], off offset:576 nt
	s_waitcnt vmcnt(0)
	v_pk_fma_f32 v[4:5], v[4:5], v[132:133], v[8:9]
	v_pk_fma_f32 v[2:3], v[2:3], v[130:131], v[6:7]
	global_store_dwordx4 v[22:23], v[2:5], off offset:576
	s_cbranch_vccnz .LBB0_940
	s_andn2_b64 vcc, exec, s[6:7]
	s_cbranch_vccnz .LBB0_939
	s_barrier
	s_branch .LBB0_939

.LBB0_1731:
	s_mul_i32 s15, s24, 0x3000
	s_mul_hi_i32 s17, s24, 0x3000
	s_and_b64 s[22:23], s[22:23], exec
	s_cselect_b32 s25, s17, 0
	s_cselect_b32 s24, s15, 0x6000
	s_lshl_b64 s[22:23], s[28:29], 14
	s_add_u32 s22, s26, s22
	s_addc_u32 s23, s27, s23
	s_lshl_b64 s[24:25], s[24:25], 2
	v_lshl_or_b32 v130, s51, 8, v163
	s_add_u32 s24, s96, s24
	v_ashrrev_i32_e32 v131, 31, v130
	s_addc_u32 s25, s97, s25
	v_lshlrev_b64 v[176:177], 2, v[130:131]
	v_lshl_add_u64 v[130:131], s[24:25], 0, v[176:177]
	v_lshl_add_u64 v[142:143], v[130:131], 0, s[12:13]
	v_add_co_u32_e32 v130, vcc, s47, v130
	v_lshl_add_u64 v[134:135], s[22:23], 0, v[150:151]
	s_nop 0
	v_addc_co_u32_e32 v131, vcc, 0, v131, vcc
	v_lshl_add_u64 v[198:199], s[22:23], 0, v[152:153]
	global_load_dwordx4 v[130:133], v[130:131], off nt
	v_lshl_add_u64 v[214:215], v[134:135], 0, v[176:177]
	v_lshl_add_u64 v[216:217], v[198:199], 0, v[176:177]
	global_load_dwordx4 v[182:185], v[214:215], off nt
	global_load_dwordx4 v[138:141], v[142:143], off offset:64 nt
	global_load_dwordx4 v[134:137], v[142:143], off offset:512 nt
	global_load_dwordx4 v[186:189], v[214:215], off offset:64 nt
	s_nop 0
	global_load_dwordx4 v[142:145], v[142:143], off offset:576 nt
	s_nop 0
	global_load_dwordx4 v[190:193], v[214:215], off offset:512 nt
	global_load_dwordx4 v[194:197], v[214:215], off offset:576 nt
	global_load_dwordx4 v[198:201], v[216:217], off nt
	global_load_dwordx4 v[202:205], v[216:217], off offset:64 nt
	global_load_dwordx4 v[206:209], v[216:217], off offset:512 nt
	global_load_dwordx4 v[210:213], v[216:217], off offset:576 nt
	v_lshl_add_u64 v[218:219], s[22:23], 0, v[154:155]
	v_lshl_add_u64 v[218:219], v[218:219], 0, v[176:177]
	s_andn2_b64 vcc, exec, s[0:1]
	s_mov_b64 s[0:1], -1
	s_waitcnt vmcnt(0)
	v_pk_fma_f32 v[124:125], v[124:125], v[140:141], v[188:189]
	v_pk_fma_f32 v[128:129], v[128:129], v[132:133], v[184:185]
	v_pk_fma_f32 v[126:127], v[126:127], v[130:131], v[182:183]
	v_pk_fma_f32 v[114:115], v[114:115], v[138:139], v[202:203]
	v_pk_fma_f32 v[122:123], v[122:123], v[138:139], v[186:187]
	v_pk_fma_f32 v[112:113], v[112:113], v[136:137], v[192:193]
	v_pk_fma_f32 v[110:111], v[110:111], v[134:135], v[190:191]
	v_pk_fma_f32 v[108:109], v[108:109], v[144:145], v[196:197]
	v_pk_fma_f32 v[106:107], v[106:107], v[142:143], v[194:195]
	v_pk_fma_f32 v[120:121], v[120:121], v[132:133], v[200:201]
	v_pk_fma_f32 v[118:119], v[118:119], v[130:131], v[198:199]
	v_pk_fma_f32 v[116:117], v[116:117], v[140:141], v[204:205]
	v_pk_fma_f32 v[104:105], v[104:105], v[136:137], v[208:209]
	v_pk_fma_f32 v[102:103], v[102:103], v[134:135], v[206:207]
	v_pk_fma_f32 v[100:101], v[100:101], v[144:145], v[212:213]
	v_pk_fma_f32 v[98:99], v[98:99], v[142:143], v[210:211]
	global_store_dwordx4 v[214:215], v[126:129], off
	global_store_dwordx4 v[214:215], v[122:125], off offset:64
	global_store_dwordx4 v[214:215], v[110:113], off offset:512
	global_store_dwordx4 v[214:215], v[106:109], off offset:576
	global_store_dwordx4 v[216:217], v[118:121], off
	global_store_dwordx4 v[216:217], v[114:117], off offset:64
	global_store_dwordx4 v[216:217], v[102:105], off offset:512
	global_store_dwordx4 v[216:217], v[98:101], off offset:576
	v_lshl_add_u64 v[114:115], s[22:23], 0, v[156:157]
	v_lshl_add_u64 v[182:183], v[114:115], 0, v[176:177]
	global_load_dwordx4 v[98:101], v[218:219], off nt
	global_load_dwordx4 v[102:105], v[218:219], off offset:64 nt
	global_load_dwordx4 v[106:109], v[218:219], off offset:512 nt
	global_load_dwordx4 v[110:113], v[218:219], off offset:576 nt
	global_load_dwordx4 v[114:117], v[182:183], off nt
	global_load_dwordx4 v[118:121], v[182:183], off offset:64 nt
	global_load_dwordx4 v[122:125], v[182:183], off offset:512 nt
	global_load_dwordx4 v[126:129], v[182:183], off offset:576 nt
	v_lshl_add_u64 v[184:185], s[22:23], 0, v[158:159]
	v_lshl_add_u64 v[184:185], v[184:185], 0, v[176:177]
	s_waitcnt vmcnt(7)
	v_pk_fma_f32 v[96:97], v[96:97], v[132:133], v[100:101]
	v_pk_fma_f32 v[94:95], v[94:95], v[130:131], v[98:99]
	s_waitcnt vmcnt(2)
	v_pk_fma_f32 v[82:83], v[82:83], v[138:139], v[118:119]
	v_pk_fma_f32 v[92:93], v[92:93], v[140:141], v[104:105]
	v_pk_fma_f32 v[90:91], v[90:91], v[138:139], v[102:103]
	v_pk_fma_f32 v[80:81], v[80:81], v[136:137], v[108:109]
	v_pk_fma_f32 v[78:79], v[78:79], v[134:135], v[106:107]
	v_pk_fma_f32 v[76:77], v[76:77], v[144:145], v[112:113]
	v_pk_fma_f32 v[74:75], v[74:75], v[142:143], v[110:111]
	v_pk_fma_f32 v[88:89], v[88:89], v[132:133], v[116:117]
	v_pk_fma_f32 v[86:87], v[86:87], v[130:131], v[114:115]
	v_pk_fma_f32 v[84:85], v[84:85], v[140:141], v[120:121]
	s_waitcnt vmcnt(1)
	v_pk_fma_f32 v[72:73], v[72:73], v[136:137], v[124:125]
	v_pk_fma_f32 v[70:71], v[70:71], v[134:135], v[122:123]
	s_waitcnt vmcnt(0)
	v_pk_fma_f32 v[68:69], v[68:69], v[144:145], v[128:129]
	v_pk_fma_f32 v[66:67], v[66:67], v[142:143], v[126:127]
	global_store_dwordx4 v[218:219], v[94:97], off
	global_store_dwordx4 v[218:219], v[90:93], off offset:64
	global_store_dwordx4 v[218:219], v[78:81], off offset:512
	global_store_dwordx4 v[218:219], v[74:77], off offset:576
	global_store_dwordx4 v[182:183], v[86:89], off
	global_store_dwordx4 v[182:183], v[82:85], off offset:64
	global_store_dwordx4 v[182:183], v[70:73], off offset:512
	global_store_dwordx4 v[182:183], v[66:69], off offset:576
	v_lshl_add_u64 v[82:83], s[22:23], 0, v[160:161]
	v_lshl_add_u64 v[98:99], v[82:83], 0, v[176:177]
	global_load_dwordx4 v[66:69], v[184:185], off nt
	global_load_dwordx4 v[70:73], v[184:185], off offset:64 nt
	global_load_dwordx4 v[74:77], v[184:185], off offset:512 nt
	global_load_dwordx4 v[78:81], v[184:185], off offset:576 nt
	global_load_dwordx4 v[82:85], v[98:99], off nt
	global_load_dwordx4 v[86:89], v[98:99], off offset:64 nt
	global_load_dwordx4 v[90:93], v[98:99], off offset:512 nt
	global_load_dwordx4 v[94:97], v[98:99], off offset:576 nt
	v_lshl_add_u64 v[100:101], s[22:23], 0, v[164:165]
	v_lshl_add_u64 v[100:101], v[100:101], 0, v[176:177]
	s_waitcnt vmcnt(7)
	v_pk_fma_f32 v[64:65], v[64:65], v[132:133], v[68:69]
	v_pk_fma_f32 v[62:63], v[62:63], v[130:131], v[66:67]
	s_waitcnt vmcnt(2)
	v_pk_fma_f32 v[50:51], v[50:51], v[138:139], v[86:87]
	v_pk_fma_f32 v[60:61], v[60:61], v[140:141], v[72:73]
	v_pk_fma_f32 v[58:59], v[58:59], v[138:139], v[70:71]
	v_pk_fma_f32 v[48:49], v[48:49], v[136:137], v[76:77]
	v_pk_fma_f32 v[46:47], v[46:47], v[134:135], v[74:75]
	v_pk_fma_f32 v[44:45], v[44:45], v[144:145], v[80:81]
	v_pk_fma_f32 v[42:43], v[42:43], v[142:143], v[78:79]
	v_pk_fma_f32 v[56:57], v[56:57], v[132:133], v[84:85]
	v_pk_fma_f32 v[54:55], v[54:55], v[130:131], v[82:83]
	v_pk_fma_f32 v[52:53], v[52:53], v[140:141], v[88:89]
	s_waitcnt vmcnt(1)
	v_pk_fma_f32 v[40:41], v[40:41], v[136:137], v[92:93]
	v_pk_fma_f32 v[38:39], v[38:39], v[134:135], v[90:91]
	s_waitcnt vmcnt(0)
	v_pk_fma_f32 v[36:37], v[36:37], v[144:145], v[96:97]
	v_pk_fma_f32 v[34:35], v[34:35], v[142:143], v[94:95]
	global_store_dwordx4 v[184:185], v[62:65], off
	global_store_dwordx4 v[184:185], v[58:61], off offset:64
	global_store_dwordx4 v[184:185], v[46:49], off offset:512
	global_store_dwordx4 v[184:185], v[42:45], off offset:576
	global_store_dwordx4 v[98:99], v[54:57], off
	global_store_dwordx4 v[98:99], v[50:53], off offset:64
	global_store_dwordx4 v[98:99], v[38:41], off offset:512
	global_store_dwordx4 v[98:99], v[34:37], off offset:576
	v_lshl_add_u64 v[50:51], s[22:23], 0, v[166:167]
	v_lshl_add_u64 v[66:67], v[50:51], 0, v[176:177]
	global_load_dwordx4 v[34:37], v[100:101], off nt
	global_load_dwordx4 v[38:41], v[100:101], off offset:64 nt
	global_load_dwordx4 v[42:45], v[100:101], off offset:512 nt
	global_load_dwordx4 v[46:49], v[100:101], off offset:576 nt
	global_load_dwordx4 v[50:53], v[66:67], off nt
	global_load_dwordx4 v[54:57], v[66:67], off offset:64 nt
	global_load_dwordx4 v[58:61], v[66:67], off offset:512 nt
	global_load_dwordx4 v[62:65], v[66:67], off offset:576 nt
	s_waitcnt vmcnt(7)
	v_pk_fma_f32 v[32:33], v[32:33], v[132:133], v[36:37]
	v_pk_fma_f32 v[30:31], v[30:31], v[130:131], v[34:35]
	s_waitcnt vmcnt(6)
	v_pk_fma_f32 v[28:29], v[28:29], v[140:141], v[40:41]
	v_pk_fma_f32 v[26:27], v[26:27], v[138:139], v[38:39]
	s_waitcnt vmcnt(5)
	v_pk_fma_f32 v[16:17], v[16:17], v[136:137], v[44:45]
	v_pk_fma_f32 v[14:15], v[14:15], v[134:135], v[42:43]
	s_waitcnt vmcnt(4)
	v_pk_fma_f32 v[12:13], v[12:13], v[144:145], v[48:49]
	v_pk_fma_f32 v[10:11], v[10:11], v[142:143], v[46:47]
	s_waitcnt vmcnt(3)
	v_pk_fma_f32 v[24:25], v[24:25], v[132:133], v[52:53]
	v_pk_fma_f32 v[22:23], v[22:23], v[130:131], v[50:51]
	s_waitcnt vmcnt(2)
	v_pk_fma_f32 v[20:21], v[20:21], v[140:141], v[56:57]
	v_pk_fma_f32 v[18:19], v[18:19], v[138:139], v[54:55]
	s_waitcnt vmcnt(1)
	v_pk_fma_f32 v[8:9], v[8:9], v[136:137], v[60:61]
	v_pk_fma_f32 v[6:7], v[6:7], v[134:135], v[58:59]
	s_waitcnt vmcnt(0)
	v_pk_fma_f32 v[4:5], v[4:5], v[144:145], v[64:65]
	v_pk_fma_f32 v[2:3], v[2:3], v[142:143], v[62:63]
	global_store_dwordx4 v[100:101], v[30:33], off
	global_store_dwordx4 v[100:101], v[26:29], off offset:64
	global_store_dwordx4 v[100:101], v[14:17], off offset:512
	global_store_dwordx4 v[100:101], v[10:13], off offset:576
	global_store_dwordx4 v[66:67], v[22:25], off
	global_store_dwordx4 v[66:67], v[18:21], off offset:64
	global_store_dwordx4 v[66:67], v[6:9], off offset:512
	global_store_dwordx4 v[66:67], v[2:5], off offset:576
	s_cbranch_vccnz .LBB0_1716
	s_andn2_b64 vcc, exec, s[6:7]
	s_cbranch_vccnz .LBB0_1715
	s_barrier
	s_branch .LBB0_1715
